# SGU position-mixing on f32 MFMA (v_mfma_f32_32x32x2_f32, f32 in/acc) with pipelined epilogue; RWKV consumers barrier every 4 chunks
# speedup vs baseline: 1.0153x; 1.0153x over previous
; #define GAS __attribute__((address_space(1)))
; __device__ __forceinline__ void sgu_job(LAS unsigned char* lds, const GAS float* Wh, const GAS float* sbias, const GAS float* VLN, GAS float* U, int m0, int h, int tid) {
;     ...
; #pragma unroll
;     for (int i = 0; i < 4; ++i) { const int t = t0 + i; const float bias = sbias[t]; GAS float* up = U + (size_t)(m0 + t) * 512 + h * 128 + d0;
;         f32x4 u0 = *(const GAS f32x4*)up, u1 = *(const GAS f32x4*)(up + 4);
;         u0.x *= acc[i][0] + bias; u0.y *= acc[i][1] + bias; u0.z *= acc[i][2] + bias; u0.w *= acc[i][3] + bias; u1.x *= acc[i][4] + bias; u1.y *= acc[i][5] + bias; u1.z *= acc[i][6] + bias; u1.w *= acc[i][7] + bias;
;         *(GAS f32x4*)up = u0; *(GAS f32x4*)(up + 4) = u1; }
.LBB0_621:
	s_mov_b32 s3, s2
	s_lshl_b32 s0, s3, 16
	s_add_u32 s24, s30, s0
	s_addc_u32 s25, s31, 0
	s_add_u32 s98, s24, 0x0
	s_addc_u32 s99, s25, 0
	global_load_dword v12, v10, s[98:99]
	global_load_dword v13, v10, s[98:99] offset:2048
	global_load_dword v14, v11, s[98:99]
	global_load_dword v15, v11, s[98:99] offset:2048
	s_add_u32 s98, s24, 0x4000
	s_addc_u32 s99, s25, 0
	global_load_dword v34, v10, s[98:99]
	global_load_dword v35, v10, s[98:99] offset:2048
	global_load_dword v36, v11, s[98:99]
	global_load_dword v37, v11, s[98:99] offset:2048
	s_add_u32 s98, s24, 0x8000
	s_addc_u32 s99, s25, 0
	global_load_dword v38, v10, s[98:99]
	global_load_dword v39, v10, s[98:99] offset:2048
	global_load_dword v40, v11, s[98:99]
	global_load_dword v41, v11, s[98:99] offset:2048
	s_add_u32 s98, s24, 0xc000
	s_addc_u32 s99, s25, 0
	global_load_dword v42, v10, s[98:99]
	global_load_dword v43, v10, s[98:99] offset:2048
	global_load_dword v44, v11, s[98:99]
	global_load_dword v45, v11, s[98:99] offset:2048
	s_nop 7
	s_waitcnt vmcnt(8)
	v_mul_f32_e32 v18, v18, v12
	v_mul_f32_e32 v19, v19, v13
	v_mul_f32_e32 v20, v20, v14
	v_mul_f32_e32 v21, v21, v15
	v_mul_f32_e32 v22, v22, v34
	v_mul_f32_e32 v23, v23, v35
	v_mul_f32_e32 v24, v24, v36
	v_mul_f32_e32 v25, v25, v37
	s_add_u32 s98, s24, 0x0
	s_addc_u32 s99, s25, 0
	global_store_dword v10, v18, s[98:99]
	global_store_dword v10, v19, s[98:99] offset:2048
	global_store_dword v11, v20, s[98:99]
	global_store_dword v11, v21, s[98:99] offset:2048
	s_add_u32 s98, s24, 0x4000
	s_addc_u32 s99, s25, 0
	global_store_dword v10, v22, s[98:99]
	global_store_dword v10, v23, s[98:99] offset:2048
	global_store_dword v11, v24, s[98:99]
	global_store_dword v11, v25, s[98:99] offset:2048
	s_sub_u32 s3, 3, s2
	s_lshl_b32 s0, s3, 16
	s_add_u32 s24, s30, s0
	s_addc_u32 s25, s31, 0
	s_add_u32 s98, s24, 0x0
	s_addc_u32 s99, s25, 0
	global_load_dword v12, v10, s[98:99]
	global_load_dword v13, v10, s[98:99] offset:2048
	global_load_dword v14, v11, s[98:99]
	global_load_dword v15, v11, s[98:99] offset:2048
	s_add_u32 s98, s24, 0x4000
	s_addc_u32 s99, s25, 0
	global_load_dword v34, v10, s[98:99]
	global_load_dword v35, v10, s[98:99] offset:2048
	global_load_dword v36, v11, s[98:99]
	global_load_dword v37, v11, s[98:99] offset:2048
	s_waitcnt vmcnt(16)
	s_mov_b32 s3, s2
	s_lshl_b32 s0, s3, 16
	s_add_u32 s24, s30, s0
	s_addc_u32 s25, s31, 0
	v_mul_f32_e32 v26, v26, v38
	v_mul_f32_e32 v27, v27, v39
	v_mul_f32_e32 v28, v28, v40
	v_mul_f32_e32 v29, v29, v41
	v_mul_f32_e32 v30, v30, v42
	v_mul_f32_e32 v31, v31, v43
	v_mul_f32_e32 v32, v32, v44
	v_mul_f32_e32 v33, v33, v45
	s_add_u32 s98, s24, 0x8000
	s_addc_u32 s99, s25, 0
	global_store_dword v10, v26, s[98:99]
	global_store_dword v10, v27, s[98:99] offset:2048
	global_store_dword v11, v28, s[98:99]
	global_store_dword v11, v29, s[98:99] offset:2048
	s_add_u32 s98, s24, 0xc000
	s_addc_u32 s99, s25, 0
	global_store_dword v10, v30, s[98:99]
	global_store_dword v10, v31, s[98:99] offset:2048
	global_store_dword v11, v32, s[98:99]
	global_store_dword v11, v33, s[98:99] offset:2048
	s_sub_u32 s3, 3, s2
	s_lshl_b32 s0, s3, 16
	s_add_u32 s24, s30, s0
	s_addc_u32 s25, s31, 0
	s_add_u32 s98, s24, 0x8000
	s_addc_u32 s99, s25, 0
	global_load_dword v38, v10, s[98:99]
	global_load_dword v39, v10, s[98:99] offset:2048
	global_load_dword v40, v11, s[98:99]
	global_load_dword v41, v11, s[98:99] offset:2048
	s_add_u32 s98, s24, 0xc000
	s_addc_u32 s99, s25, 0
	global_load_dword v42, v10, s[98:99]
	global_load_dword v43, v10, s[98:99] offset:2048
	global_load_dword v44, v11, s[98:99]
	global_load_dword v45, v11, s[98:99] offset:2048
	s_waitcnt vmcnt(16)
	v_mul_f32_e32 v148, v148, v12
	v_mul_f32_e32 v149, v149, v13
	v_mul_f32_e32 v150, v150, v14
	v_mul_f32_e32 v151, v151, v15
	v_mul_f32_e32 v152, v152, v34
	v_mul_f32_e32 v153, v153, v35
	v_mul_f32_e32 v154, v154, v36
	v_mul_f32_e32 v155, v155, v37
	s_add_u32 s98, s24, 0x0
	s_addc_u32 s99, s25, 0
	global_store_dword v10, v148, s[98:99]
	global_store_dword v10, v149, s[98:99] offset:2048
	global_store_dword v11, v150, s[98:99]
	global_store_dword v11, v151, s[98:99] offset:2048
	s_add_u32 s98, s24, 0x4000
	s_addc_u32 s99, s25, 0
	global_store_dword v10, v152, s[98:99]
	global_store_dword v10, v153, s[98:99] offset:2048
	global_store_dword v11, v154, s[98:99]
	global_store_dword v11, v155, s[98:99] offset:2048
	s_waitcnt vmcnt(8)
	v_mul_f32_e32 v156, v156, v38
	v_mul_f32_e32 v157, v157, v39
	v_mul_f32_e32 v158, v158, v40
	v_mul_f32_e32 v159, v159, v41
	v_mul_f32_e32 v160, v160, v42
	v_mul_f32_e32 v161, v161, v43
	v_mul_f32_e32 v162, v162, v44
	v_mul_f32_e32 v163, v163, v45
	s_add_u32 s98, s24, 0x8000
	s_addc_u32 s99, s25, 0
	global_store_dword v10, v156, s[98:99]
	global_store_dword v10, v157, s[98:99] offset:2048
	global_store_dword v11, v158, s[98:99]
	global_store_dword v11, v159, s[98:99] offset:2048
	s_add_u32 s98, s24, 0xc000
	s_addc_u32 s99, s25, 0
	global_store_dword v10, v160, s[98:99]
	global_store_dword v10, v161, s[98:99] offset:2048
	global_store_dword v11, v162, s[98:99]
	global_store_dword v11, v163, s[98:99] offset:2048
	v_readlane_b32 s0, v252, 15
	s_nop 3
	s_add_i32 s16, s16, s0
	s_cmpk_lt_i32 s16, 0x100
	s_barrier
	s_cbranch_scc0 .LBB0_626
; __device__ __forceinline__ void sgu_job(LAS unsigned char* lds, const GAS float* Wh, const GAS float* sbias, const GAS float* VLN, GAS float* U, int m0, int h, int tid) {
;     ...
;     for (int i0 = 0; i0 < 32; i0 += 16) { float tw[16], tv[16];
; #pragma unroll
;         for (int i = 0; i < 16; ++i) { const int idx = tid + 512 * (i0 + i), t = idx >> 7, s = idx & 127; tw[i] = Wh[idx]; tv[i] = VLN[(size_t)(m0 + t) * 512 + h * 128 + s]; }
; #pragma unroll
;         for (int i = 0; i < 16; ++i) { const int idx = tid + 512 * (i0 + i), t = idx >> 7, s = idx & 127; WL[t * 132 + s] = (s <= t) ? tw[i] : 0.f; VT[idx] = tv[i]; } }
.LBB0_622:
	s_and_b32 s23, s16, 3
	s_lshl_b32 s0, s23, 14
	s_or_b32 s82, s0, s15
	s_lshl_b32 s0, s16, 5
	s_and_b32 s17, s0, 0xffffff80
	v_add_u32_e32 v14, s17, v46
	s_lshl_b32 s0, s23, 9
	s_mov_b32 s1, s83
	v_ashrrev_i32_e32 v15, 31, v14
	v_lshl_add_u64 v[10:11], v[0:1], 0, s[0:1]
	v_lshlrev_b64 v[14:15], 11, v[14:15]
	v_lshl_add_u64 v[12:13], s[82:83], 2, v[8:9]
	v_lshl_add_u64 v[14:15], v[10:11], 0, v[14:15]
	global_load_dword v22, v[12:13], off
	global_load_dword v23, v[14:15], off
	global_load_dword v24, v[12:13], off offset:2048
	v_add_u32_e32 v14, s17, v47
	v_ashrrev_i32_e32 v15, 31, v14
	v_lshlrev_b64 v[14:15], 11, v[14:15]
	v_lshl_add_u64 v[14:15], v[10:11], 0, v[14:15]
	s_movk_i32 s0, 0x1000
	global_load_dword v25, v[14:15], off
	v_add_co_u32_e32 v14, vcc, s0, v12
	v_add_u32_e32 v20, s17, v48
	s_nop 0
	v_addc_co_u32_e32 v15, vcc, 0, v13, vcc
	v_ashrrev_i32_e32 v21, 31, v20
	v_add_co_u32_e32 v18, vcc, s36, v12
	v_lshlrev_b64 v[20:21], 11, v[20:21]
	s_nop 0
	v_addc_co_u32_e32 v19, vcc, 0, v13, vcc
	v_lshl_add_u64 v[20:21], v[10:11], 0, v[20:21]
	global_load_dword v26, v[18:19], off offset:-4096
	global_load_dword v27, v[20:21], off
	global_load_dword v28, v[14:15], off offset:2048
	v_add_u32_e32 v14, s17, v49
	v_ashrrev_i32_e32 v15, 31, v14
	v_lshlrev_b64 v[14:15], 11, v[14:15]
	v_lshl_add_u64 v[14:15], v[10:11], 0, v[14:15]
	global_load_dword v29, v[14:15], off
	global_load_dword v30, v[18:19], off
	v_add_u32_e32 v14, s17, v50
	v_ashrrev_i32_e32 v15, 31, v14
	v_lshlrev_b64 v[14:15], 11, v[14:15]
	v_lshl_add_u64 v[14:15], v[10:11], 0, v[14:15]
	global_load_dword v31, v[14:15], off
	global_load_dword v32, v[18:19], off offset:2048
	v_add_u32_e32 v14, s17, v51
	v_ashrrev_i32_e32 v15, 31, v14
	v_lshlrev_b64 v[14:15], 11, v[14:15]
	v_lshl_add_u64 v[14:15], v[10:11], 0, v[14:15]
	s_movk_i32 s0, 0x3000
	global_load_dword v33, v[14:15], off
	v_add_co_u32_e32 v14, vcc, s0, v12
	v_add_u32_e32 v20, s17, v52
	s_nop 0
	v_addc_co_u32_e32 v15, vcc, 0, v13, vcc
	v_ashrrev_i32_e32 v21, 31, v20
	v_add_co_u32_e32 v18, vcc, s37, v12
	v_lshlrev_b64 v[20:21], 11, v[20:21]
	s_nop 0
	v_addc_co_u32_e32 v19, vcc, 0, v13, vcc
	v_lshl_add_u64 v[20:21], v[10:11], 0, v[20:21]
	global_load_dword v34, v[18:19], off offset:-4096
	global_load_dword v35, v[20:21], off
	global_load_dword v36, v[14:15], off offset:2048
	v_add_u32_e32 v14, s17, v53
	v_ashrrev_i32_e32 v15, 31, v14
	v_lshlrev_b64 v[14:15], 11, v[14:15]
	v_lshl_add_u64 v[14:15], v[10:11], 0, v[14:15]
	global_load_dword v37, v[14:15], off
	global_load_dword v38, v[18:19], off
	v_add_u32_e32 v14, s17, v54
	v_ashrrev_i32_e32 v15, 31, v14
	v_lshlrev_b64 v[14:15], 11, v[14:15]
	v_lshl_add_u64 v[14:15], v[10:11], 0, v[14:15]
	global_load_dword v39, v[14:15], off
	global_load_dword v40, v[18:19], off offset:2048
	v_add_u32_e32 v14, s17, v55
	v_ashrrev_i32_e32 v15, 31, v14
	v_lshlrev_b64 v[14:15], 11, v[14:15]
	v_lshl_add_u64 v[14:15], v[10:11], 0, v[14:15]
	s_movk_i32 s0, 0x5000
	global_load_dword v41, v[14:15], off
	v_add_co_u32_e32 v14, vcc, s0, v12
	v_add_u32_e32 v20, s17, v56
	s_nop 0
	v_addc_co_u32_e32 v15, vcc, 0, v13, vcc
	s_movk_i32 s0, 0x6000
	v_ashrrev_i32_e32 v21, 31, v20
	v_add_co_u32_e32 v18, vcc, s0, v12
	v_lshlrev_b64 v[20:21], 11, v[20:21]
	s_nop 0
	v_addc_co_u32_e32 v19, vcc, 0, v13, vcc
	v_lshl_add_u64 v[20:21], v[10:11], 0, v[20:21]
	global_load_dword v42, v[18:19], off offset:-4096
	global_load_dword v43, v[20:21], off
	global_load_dword v44, v[14:15], off offset:2048
	v_add_u32_e32 v14, s17, v57
	v_ashrrev_i32_e32 v15, 31, v14
	v_lshlrev_b64 v[14:15], 11, v[14:15]
	v_lshl_add_u64 v[14:15], v[10:11], 0, v[14:15]
	global_load_dword v45, v[14:15], off
	global_load_dword v147, v[18:19], off
	v_add_u32_e32 v14, s17, v58
	v_ashrrev_i32_e32 v15, 31, v14
	v_lshlrev_b64 v[14:15], 11, v[14:15]
	v_lshl_add_u64 v[14:15], v[10:11], 0, v[14:15]
	global_load_dword v148, v[14:15], off
	global_load_dword v149, v[18:19], off offset:2048
	v_add_u32_e32 v14, s17, v59
	v_ashrrev_i32_e32 v15, 31, v14
	v_lshlrev_b64 v[14:15], 11, v[14:15]
	v_lshl_add_u64 v[14:15], v[10:11], 0, v[14:15]
	s_movk_i32 s0, 0x7000
	global_load_dword v150, v[14:15], off
	v_add_co_u32_e32 v14, vcc, s0, v12
	s_mov_b32 s0, 0x8000
	s_nop 0
	v_addc_co_u32_e32 v15, vcc, 0, v13, vcc
	v_add_u32_e32 v20, s17, v60
	v_add_co_u32_e32 v18, vcc, s0, v12
	v_ashrrev_i32_e32 v21, 31, v20
	s_nop 0
	v_addc_co_u32_e32 v19, vcc, 0, v13, vcc
	v_lshlrev_b64 v[20:21], 11, v[20:21]
	global_load_dword v151, v[18:19], off offset:-4096
	v_lshl_add_u64 v[20:21], v[10:11], 0, v[20:21]
	global_load_dword v20, v[20:21], off
	s_nop 0
	global_load_dword v21, v[14:15], off offset:2048
	v_add_u32_e32 v14, s17, v61
	v_ashrrev_i32_e32 v15, 31, v14
	v_lshlrev_b64 v[14:15], 11, v[14:15]
	v_lshl_add_u64 v[14:15], v[10:11], 0, v[14:15]
	global_load_dword v14, v[14:15], off
	s_waitcnt vmcnt(0)
; __device__ __forceinline__ void sgu_job(LAS unsigned char* lds, const GAS float* Wh, const GAS float* sbias, const GAS float* VLN, GAS float* U, int m0, int h, int tid) {
;     ...
;     for (int i0 = 0; i0 < 32; i0 += 16) { float tw[16], tv[16];
; #pragma unroll
;         for (int i = 0; i < 16; ++i) { const int idx = tid + 512 * (i0 + i), t = idx >> 7, s = idx & 127; tw[i] = Wh[idx]; tv[i] = VLN[(size_t)(m0 + t) * 512 + h * 128 + s]; }
; #pragma unroll
;         for (int i = 0; i < 16; ++i) { const int idx = tid + 512 * (i0 + i), t = idx >> 7, s = idx & 127; WL[t * 132 + s] = (s <= t) ? tw[i] : 0.f; VT[idx] = tv[i]; } }
	v_cndmask_b32_e64 v15, v22, 0, s[4:5]
	ds_write_b32 v115, v15
	ds_write_b32 v62, v23
	v_cndmask_b32_e64 v15, v24, 0, s[40:41]
	ds_write_b32 v116, v15
	ds_write_b32 v63, v25
	v_cndmask_b32_e64 v15, v26, 0, s[42:43]
	ds_write_b32 v117, v15
	ds_write_b32 v64, v27
	v_cndmask_b32_e64 v15, v28, 0, s[44:45]
	ds_write_b32 v118, v15
	ds_write_b32 v65, v29
	v_cndmask_b32_e64 v15, v30, 0, s[46:47]
	ds_write_b32 v119, v15
	ds_write_b32 v66, v31
	v_cndmask_b32_e64 v15, v32, 0, s[48:49]
	ds_write_b32 v120, v15
	ds_write_b32 v67, v33
	v_cndmask_b32_e64 v15, v34, 0, s[50:51]
	ds_write_b32 v121, v15
	ds_write_b32 v68, v35
	v_cndmask_b32_e64 v15, v36, 0, s[52:53]
	ds_write_b32 v122, v15
	ds_write_b32 v69, v37
	v_cndmask_b32_e64 v15, v38, 0, s[54:55]
	ds_write_b32 v123, v15
	ds_write_b32 v70, v39
	v_cndmask_b32_e64 v15, v40, 0, s[56:57]
	ds_write_b32 v124, v15
	ds_write_b32 v71, v41
	s_mov_b32 s0, 0x9000
	v_add_u32_e32 v22, s17, v80
	v_ashrrev_i32_e32 v23, 31, v22
	v_lshlrev_b64 v[22:23], 11, v[22:23]
	v_lshl_add_u64 v[22:23], v[10:11], 0, v[22:23]
	v_cndmask_b32_e64 v15, v42, 0, s[58:59]
	ds_write_b32 v125, v15
	ds_write_b32 v72, v43
	v_cndmask_b32_e64 v15, v44, 0, s[60:61]
	ds_write_b32 v126, v15
	ds_write_b32 v73, v45
	v_cndmask_b32_e64 v15, v147, 0, s[62:63]
	ds_write_b32 v127, v15
	ds_write_b32 v74, v148
	v_cndmask_b32_e64 v15, v149, 0, s[64:65]
	ds_write_b32 v128, v15
	ds_write_b32 v75, v150
	v_cndmask_b32_e64 v15, v151, 0, s[66:67]
	ds_write_b32 v129, v15
	ds_write_b32 v76, v20
	v_add_u32_e32 v20, s17, v78
	v_cndmask_b32_e64 v15, v21, 0, s[68:69]
	v_ashrrev_i32_e32 v21, 31, v20
	v_lshlrev_b64 v[20:21], 11, v[20:21]
	ds_write_b32 v130, v15
	ds_write_b32 v77, v14
	v_lshl_add_u64 v[20:21], v[10:11], 0, v[20:21]
	global_load_dword v14, v[18:19], off
	global_load_dword v15, v[20:21], off
	global_load_dword v24, v[18:19], off offset:2048
	v_add_u32_e32 v18, s17, v79
	v_ashrrev_i32_e32 v19, 31, v18
	v_lshlrev_b64 v[18:19], 11, v[18:19]
	v_lshl_add_u64 v[18:19], v[10:11], 0, v[18:19]
	global_load_dword v25, v[18:19], off
	v_add_co_u32_e32 v18, vcc, s0, v12
	s_mov_b32 s0, 0xa000
	s_nop 0
	v_addc_co_u32_e32 v19, vcc, 0, v13, vcc
	v_add_co_u32_e32 v20, vcc, s0, v12
	s_mov_b32 s0, 0xb000
	s_nop 0
	v_addc_co_u32_e32 v21, vcc, 0, v13, vcc
	global_load_dword v26, v[20:21], off offset:-4096
	global_load_dword v27, v[22:23], off
	global_load_dword v28, v[18:19], off offset:2048
	v_add_u32_e32 v18, s17, v81
	v_ashrrev_i32_e32 v19, 31, v18
	v_lshlrev_b64 v[18:19], 11, v[18:19]
	v_lshl_add_u64 v[18:19], v[10:11], 0, v[18:19]
	global_load_dword v29, v[18:19], off
	global_load_dword v30, v[20:21], off
	v_add_u32_e32 v18, s17, v82
	v_ashrrev_i32_e32 v19, 31, v18
	v_lshlrev_b64 v[18:19], 11, v[18:19]
	v_lshl_add_u64 v[18:19], v[10:11], 0, v[18:19]
	global_load_dword v31, v[18:19], off
	global_load_dword v32, v[20:21], off offset:2048
	v_add_u32_e32 v18, s17, v83
	v_ashrrev_i32_e32 v19, 31, v18
	v_lshlrev_b64 v[18:19], 11, v[18:19]
	v_lshl_add_u64 v[18:19], v[10:11], 0, v[18:19]
	global_load_dword v33, v[18:19], off
	v_add_co_u32_e32 v18, vcc, s0, v12
	v_add_u32_e32 v22, s17, v84
	s_nop 0
	v_addc_co_u32_e32 v19, vcc, 0, v13, vcc
	s_mov_b32 s0, 0xc000
	v_ashrrev_i32_e32 v23, 31, v22
	v_add_co_u32_e32 v20, vcc, s0, v12
	v_lshlrev_b64 v[22:23], 11, v[22:23]
	s_nop 0
	v_addc_co_u32_e32 v21, vcc, 0, v13, vcc
	v_lshl_add_u64 v[22:23], v[10:11], 0, v[22:23]
	global_load_dword v34, v[20:21], off offset:-4096
	global_load_dword v35, v[22:23], off
	global_load_dword v36, v[18:19], off offset:2048
	v_add_u32_e32 v18, s17, v85
	v_ashrrev_i32_e32 v19, 31, v18
	v_lshlrev_b64 v[18:19], 11, v[18:19]
	v_lshl_add_u64 v[18:19], v[10:11], 0, v[18:19]
	global_load_dword v37, v[18:19], off
	global_load_dword v38, v[20:21], off
	v_add_u32_e32 v18, s17, v86
	v_ashrrev_i32_e32 v19, 31, v18
	v_lshlrev_b64 v[18:19], 11, v[18:19]
	v_lshl_add_u64 v[18:19], v[10:11], 0, v[18:19]
	global_load_dword v39, v[18:19], off
	global_load_dword v40, v[20:21], off offset:2048
	v_add_u32_e32 v18, s17, v87
	v_ashrrev_i32_e32 v19, 31, v18
	v_lshlrev_b64 v[18:19], 11, v[18:19]
	v_lshl_add_u64 v[18:19], v[10:11], 0, v[18:19]
	s_mov_b32 s0, 0xd000
	global_load_dword v41, v[18:19], off
	v_add_co_u32_e32 v18, vcc, s0, v12
	v_add_u32_e32 v22, s17, v88
	s_nop 0
	v_addc_co_u32_e32 v19, vcc, 0, v13, vcc
	s_mov_b32 s0, 0xe000
	v_ashrrev_i32_e32 v23, 31, v22
	v_add_co_u32_e32 v20, vcc, s0, v12
	v_lshlrev_b64 v[22:23], 11, v[22:23]
	s_nop 0
	v_addc_co_u32_e32 v21, vcc, 0, v13, vcc
	v_lshl_add_u64 v[22:23], v[10:11], 0, v[22:23]
	global_load_dword v42, v[20:21], off offset:-4096
	s_nop 0
	global_load_dword v22, v[22:23], off
	s_nop 0
	global_load_dword v23, v[18:19], off offset:2048
	v_add_u32_e32 v18, s17, v89
	v_ashrrev_i32_e32 v19, 31, v18
	v_lshlrev_b64 v[18:19], 11, v[18:19]
	v_lshl_add_u64 v[18:19], v[10:11], 0, v[18:19]
	global_load_dword v43, v[18:19], off
	global_load_dword v44, v[20:21], off
	v_add_u32_e32 v18, s17, v90
	v_ashrrev_i32_e32 v19, 31, v18
	v_lshlrev_b64 v[18:19], 11, v[18:19]
	v_lshl_add_u64 v[18:19], v[10:11], 0, v[18:19]
	global_load_dword v45, v[18:19], off
	s_nop 0
	global_load_dword v20, v[20:21], off offset:2048
	v_add_u32_e32 v18, s17, v91
	v_ashrrev_i32_e32 v19, 31, v18
	v_lshlrev_b64 v[18:19], 11, v[18:19]
	v_lshl_add_u64 v[18:19], v[10:11], 0, v[18:19]
	global_load_dword v21, v[18:19], off
	v_add_u32_e32 v18, s17, v92
	s_mov_b32 s0, 0xf000
	v_ashrrev_i32_e32 v19, 31, v18
	v_add_co_u32_e32 v12, vcc, s0, v12
	v_lshlrev_b64 v[18:19], 11, v[18:19]
	s_nop 0
	v_addc_co_u32_e32 v13, vcc, 0, v13, vcc
	v_lshl_add_u64 v[18:19], v[10:11], 0, v[18:19]
	global_load_dword v147, v[12:13], off
	s_nop 0
	global_load_dword v18, v[18:19], off
	s_nop 0
	global_load_dword v19, v[12:13], off offset:2048
	v_add_u32_e32 v12, s17, v93
	v_ashrrev_i32_e32 v13, 31, v12
	v_lshlrev_b64 v[12:13], 11, v[12:13]
	v_lshl_add_u64 v[10:11], v[10:11], 0, v[12:13]
	global_load_dword v10, v[10:11], off
	s_waitcnt vmcnt(31)
; #define LAS __attribute__((address_space(3)))
; __device__ __forceinline__ void sgu_job(LAS unsigned char* lds, const GAS float* Wh, const GAS float* sbias, const GAS float* VLN, GAS float* U, int m0, int h, int tid) {
;     ...
;     __syncthreads();
;     const int t0 = (tid >> 4) * 4, d0 = (tid & 15) * 8;
;     float acc[4][8];
; #pragma unroll
;     for (int i = 0; i < 4; ++i)
; #pragma unroll
;         for (int j = 0; j < 8; ++j) acc[i][j] = 0.f;
;     for (int s = 0; s <= t0 + 3; ++s) {
;         const f32x4 v0 = *(const LAS f32x4*)(VT + s * 128 + d0), v1 = *(const LAS f32x4*)(VT + s * 128 + d0 + 4);
; #pragma unroll
;         for (int i = 0; i < 4; ++i) { const float w = WL[(t0 + i) * 132 + s];
;             acc[i][0] += w * v0.x; acc[i][1] += w * v0.y; acc[i][2] += w * v0.z; acc[i][3] += w * v0.w; acc[i][4] += w * v1.x; acc[i][5] += w * v1.y; acc[i][6] += w * v1.z; acc[i][7] += w * v1.w; }
;     }
	v_cndmask_b32_e64 v11, v14, 0, s[70:71]
	ds_write_b32 v131, v11
	s_waitcnt vmcnt(30)
	ds_write_b32 v94, v15
	s_waitcnt vmcnt(29)
	v_cndmask_b32_e64 v11, v24, 0, s[72:73]
	ds_write_b32 v132, v11
	s_waitcnt vmcnt(28)
	ds_write_b32 v95, v25
	s_waitcnt vmcnt(27)
	v_cndmask_b32_e64 v11, v26, 0, s[74:75]
	ds_write_b32 v133, v11
	s_waitcnt vmcnt(26)
	ds_write_b32 v96, v27
	s_waitcnt vmcnt(25)
	v_cndmask_b32_e64 v11, v28, 0, s[76:77]
	ds_write_b32 v134, v11
	s_waitcnt vmcnt(24)
	ds_write_b32 v97, v29
	s_waitcnt vmcnt(23)
	v_cndmask_b32_e64 v11, v30, 0, s[78:79]
	ds_write_b32 v135, v11
	s_waitcnt vmcnt(22)
	ds_write_b32 v98, v31
	s_waitcnt vmcnt(21)
	v_cndmask_b32_e64 v11, v32, 0, s[80:81]
	ds_write_b32 v136, v11
	s_waitcnt vmcnt(20)
	ds_write_b32 v99, v33
	s_waitcnt vmcnt(19)
	v_cndmask_b32_e64 v11, v34, 0, s[10:11]
	ds_write_b32 v137, v11
	s_waitcnt vmcnt(18)
	ds_write_b32 v100, v35
	s_waitcnt vmcnt(17)
	v_cndmask_b32_e64 v11, v36, 0, s[84:85]
	ds_write_b32 v138, v11
	s_waitcnt vmcnt(16)
	ds_write_b32 v101, v37
	s_waitcnt vmcnt(15)
	v_cndmask_b32_e64 v11, v38, 0, s[86:87]
	ds_write_b32 v139, v11
	s_waitcnt vmcnt(14)
	ds_write_b32 v102, v39
	s_waitcnt vmcnt(13)
	v_cndmask_b32_e64 v11, v40, 0, s[88:89]
	ds_write_b32 v140, v11
	s_waitcnt vmcnt(12)
	ds_write_b32 v103, v41
	v_mov_b32_e32 v41, 0
	v_mov_b32_e32 v40, v41
	v_mov_b32_e32 v37, v41
	v_mov_b32_e32 v36, v41
	v_mov_b32_e32 v39, v41
	v_mov_b32_e32 v38, v41
	v_mov_b32_e32 v35, v41
	v_mov_b32_e32 v34, v41
	v_mov_b32_e32 v33, v41
	v_mov_b32_e32 v32, v41
	v_mov_b32_e32 v31, v41
	v_mov_b32_e32 v30, v41
	v_mov_b32_e32 v29, v41
	v_mov_b32_e32 v28, v41
	s_waitcnt vmcnt(11)
	v_cndmask_b32_e64 v11, v42, 0, s[90:91]
	ds_write_b32 v141, v11
	s_waitcnt vmcnt(10)
	ds_write_b32 v104, v22
	s_waitcnt vmcnt(9)
	v_cndmask_b32_e64 v11, v23, 0, s[92:93]
	ds_write_b32 v142, v11
	s_waitcnt vmcnt(8)
	ds_write_b32 v105, v43
	s_waitcnt vmcnt(7)
	v_cndmask_b32_e64 v11, v44, 0, s[94:95]
	ds_write_b32 v143, v11
	s_waitcnt vmcnt(6)
	ds_write_b32 v106, v45
	s_waitcnt vmcnt(5)
	v_cndmask_b32_e64 v11, v20, 0, s[96:97]
	ds_write_b32 v144, v11
	s_waitcnt vmcnt(4)
	ds_write_b32 v107, v21
	v_mov_b32_e32 v43, v41
	v_mov_b32_e32 v42, v41
	v_mov_b32_e32 v27, v41
	v_mov_b32_e32 v26, v41
	v_mov_b32_e32 v25, v41
	v_mov_b32_e32 v24, v41
	v_mov_b32_e32 v23, v41
	v_mov_b32_e32 v22, v41
	v_mov_b32_e32 v21, v41
	v_mov_b32_e32 v20, v41
	s_waitcnt vmcnt(3)
	v_cndmask_b32_e64 v11, v147, 0, s[6:7]
	ds_write_b32 v145, v11
	s_waitcnt vmcnt(2)
	ds_write_b32 v108, v18
	s_waitcnt vmcnt(1)
	v_cndmask_b32_e64 v11, v19, 0, s[8:9]
	ds_write_b32 v146, v11
	s_waitcnt vmcnt(0)
	ds_write_b32 v109, v10
	v_mov_b32_e32 v19, v41
	v_mov_b32_e32 v18, v41
	v_mov_b32_e32 v15, v41
	v_mov_b32_e32 v14, v41
	v_mov_b32_e32 v13, v41
	v_mov_b32_e32 v12, v41
	v_mov_b32_e32 v11, v41
	v_mov_b32_e32 v10, v41
	s_waitcnt lgkmcnt(0)
	s_barrier
	s_mov_b64 exec, -1
	v_readlane_b32 s24, v251, 2
	v_readlane_b32 s25, v251, 3
	v_readlane_b32 s3, v254, 10
	v_readfirstlane_b32 s0, v195
	s_nop 3
	s_load_dwordx2 s[30:31], s[24:25], 0x138
	s_load_dwordx2 s[32:33], s[24:25], 0xd8
	s_lshr_b32 s0, s0, 6
	s_lshr_b32 s1, s0, 1
	s_and_b32 s2, s0, 1
	v_and_b32_e32 v10, 63, v195
	v_and_b32_e32 v11, 31, v10
	v_lshrrev_b32_e32 v12, 5, v10
	v_mul_u32_u24_e32 v176, 0x210, v11
	v_lshl_add_u32 v176, v12, 4, v176
	v_lshlrev_b32_e32 v177, 11, v12
	v_lshl_add_u32 v177, v11, 2, v177
	s_lshl_b32 s0, s1, 7
	s_add_u32 s98, s0, 0x10800
	v_add_u32_e32 v177, s98, v177
	v_lshlrev_b32_e32 v147, 2, v11
	v_cmp_gt_u32_e32 vcc, 32, v10
	v_mov_b32_e32 v35, 1.0
	v_lshlrev_b32_e32 v10, 13, v12
	v_lshl_add_u32 v11, v11, 2, s0
	v_add_u32_e32 v10, v10, v11
	v_add_u32_e32 v11, 0x1000, v10
	s_lshr_b32 s0, s16, 6
	s_bfe_u32 s1, s16, 0x40002
	s_and_b32 s98, s16, 3
	s_lshl_b32 s0, s0, 11
	s_lshl_b32 s1, s1, 7
	s_add_u32 s0, s0, s1
	s_lshl_b32 s0, s0, 11
	s_lshl_b32 s1, s98, 9
	s_add_u32 s0, s0, s1
	s_lshl_b32 s3, s3, 2
	s_add_u32 s3, s3, s98
	s_lshl_b32 s3, s3, 9
	s_waitcnt lgkmcnt(0)
	s_add_u32 s30, s30, 0x24600000
	s_addc_u32 s31, s31, 0
	s_add_u32 s30, s30, s0
	s_addc_u32 s31, s31, 0
	s_add_u32 s32, s32, s3
	s_addc_u32 s33, s33, 0
	s_lshl_b32 s0, s2, 7
	s_add_u32 s24, s32, s0
	s_addc_u32 s25, s33, 0
	global_load_dword v44, v147, s[24:25]
	s_sub_u32 s0, 3, s2
	s_lshl_b32 s0, s0, 7
	s_add_u32 s24, s32, s0
	s_addc_u32 s25, s33, 0
	global_load_dword v45, v147, s[24:25]
	v_mov_b32_e32 v18, 0
	v_mov_b32_e32 v19, 0
	v_mov_b32_e32 v20, 0
	v_mov_b32_e32 v21, 0
	v_mov_b32_e32 v22, 0
	v_mov_b32_e32 v23, 0
	v_mov_b32_e32 v24, 0
	v_mov_b32_e32 v25, 0
	v_mov_b32_e32 v26, 0
	v_mov_b32_e32 v27, 0
	v_mov_b32_e32 v28, 0
	v_mov_b32_e32 v29, 0
	v_mov_b32_e32 v30, 0
	v_mov_b32_e32 v31, 0
	v_mov_b32_e32 v32, 0
	v_mov_b32_e32 v33, 0
	v_mov_b32_e32 v148, 0
	v_mov_b32_e32 v149, 0
	v_mov_b32_e32 v150, 0
	v_mov_b32_e32 v151, 0
	v_mov_b32_e32 v152, 0
	v_mov_b32_e32 v153, 0
	v_mov_b32_e32 v154, 0
	v_mov_b32_e32 v155, 0
	v_mov_b32_e32 v156, 0
	v_mov_b32_e32 v157, 0
	v_mov_b32_e32 v158, 0
	v_mov_b32_e32 v159, 0
	v_mov_b32_e32 v160, 0
	v_mov_b32_e32 v161, 0
	v_mov_b32_e32 v162, 0
	v_mov_b32_e32 v163, 0
	s_mov_b32 s0, s2
	s_mul_i32 s1, s0, 0x4200
	v_add_u32_e32 v172, s1, v176
	v_mov_b32_e32 v173, v177
	v_add_u32_e32 v174, 0x400, v177
	s_add_u32 s3, s0, 1
	s_lshl_b32 s3, s3, 2
.Lsg_loop_a:
	ds_read_b128 v[36:39], v172
	ds_read2_b32 v[40:41], v173 offset1:128
	ds_read2_b32 v[42:43], v174 offset1:128
	v_add_u32_e32 v172, 32, v172
	v_add_u32_e32 v173, 0x1000, v173
	v_add_u32_e32 v174, 0x1000, v174
	s_sub_u32 s3, s3, 1
	s_waitcnt lgkmcnt(0)
	v_mfma_f32_32x32x2_f32 v[18:33], v36, v40, v[18:33]
	v_mfma_f32_32x32x2_f32 v[18:33], v37, v41, v[18:33]
	v_mfma_f32_32x32x2_f32 v[18:33], v38, v42, v[18:33]
	v_mfma_f32_32x32x2_f32 v[18:33], v39, v43, v[18:33]
	s_cmp_lg_u32 s3, 0
	s_cbranch_scc1 .Lsg_loop_a
	s_waitcnt vmcnt(0)
	v_cndmask_b32_e32 v44, 0, v44, vcc
	s_nop 1
	v_mfma_f32_32x32x2_f32 v[18:33], v44, v35, v[18:33]
	s_sub_u32 s0, 3, s2
	s_mul_i32 s1, s0, 0x4200
	v_add_u32_e32 v172, s1, v176
	v_mov_b32_e32 v173, v177
	v_add_u32_e32 v174, 0x400, v177
	s_add_u32 s3, s0, 1
	s_lshl_b32 s3, s3, 2
.Lsg_loop_b:
	ds_read_b128 v[36:39], v172
	ds_read2_b32 v[40:41], v173 offset1:128
	ds_read2_b32 v[42:43], v174 offset1:128
	v_add_u32_e32 v172, 32, v172
	v_add_u32_e32 v173, 0x1000, v173
	v_add_u32_e32 v174, 0x1000, v174
	s_sub_u32 s3, s3, 1
	s_waitcnt lgkmcnt(0)
	v_mfma_f32_32x32x2_f32 v[148:163], v36, v40, v[148:163]
	v_mfma_f32_32x32x2_f32 v[148:163], v37, v41, v[148:163]
	v_mfma_f32_32x32x2_f32 v[148:163], v38, v42, v[148:163]
	v_mfma_f32_32x32x2_f32 v[148:163], v39, v43, v[148:163]
	s_cmp_lg_u32 s3, 0
	s_cbranch_scc1 .Lsg_loop_b
	s_waitcnt vmcnt(0)
	v_cndmask_b32_e32 v45, 0, v45, vcc
	s_nop 1
	v_mfma_f32_32x32x2_f32 v[148:163], v45, v35, v[148:163]
	s_branch .LBB0_621

; #define LAS __attribute__((address_space(3)))
; #define R4_ISSUE(cc, slot) do { const GAS float* g_ = gp + (size_t)(cc) * 2048; LAS float* l_ = ring + (slot) * 1536; _Pragma("unroll") for (int i_ = 0; i_ < 6; ++i_) \
;         __builtin_amdgcn_global_load_lds((const GAS unsigned*)(g_ + off[i_]), (LAS unsigned*)(l_ + i_ * 256), 16, 0, 0); } while (0)
; #define R4_LOAD(o, sb_) do { const LAS float* sb = (sb_); (o).r = *(const LAS f32x4*)(sb + cgp * 4); (o).w = *(const LAS f32x4*)(sb + 64 + cgp * 4); (o).k = *(const LAS f32x4*)(sb + 128 + cgp * 4); \
;         (o).a = *(const LAS f32x4*)(sb + 256 + cgp * 4); (o).b = *(const LAS f32x4*)(sb + 320 + cgp * 4); (o).vv = sb[192 + rq * 4 + rl]; asm volatile("" ::: "memory"); } while (0)
; __device__ __forceinline__ void rwkv_prompt_wave4(LAS float* ring, const GAS float* RW, int mbase, int h, int rq, GAS float* Sout, GAS float* YR, int lane) {
;     ...
;     for (int ci = 0; ci < NCH; ++ci) {
;         { const int cn = ci + 3; const int cl = cn < NCH ? cn : NCH - 1; R4_ISSUE(cl, cn % R4_NS); }
;         const LAS float* cb = ring + (ci % R4_NS) * 1536; const LAS float* nb = ring + ((ci + 1) % R4_NS) * 1536;
;         R4_LOAD(oC, cb + 768);  R4_STEP(oA, 0);
.LBB0_707:
	s_and_b32 s0, s21, 3
	s_cmp_lg_u32 s0, 0
	s_cbranch_scc1 .Lrw_nobar
	s_cmp_eq_u32 s21, 0
	s_cbranch_scc1 .Lrw_nobar
	s_barrier
; #define LAS __attribute__((address_space(3)))
; #define R4_ISSUE(cc, slot) do { const GAS float* g_ = gp + (size_t)(cc) * 2048; LAS float* l_ = ring + (slot) * 1536; _Pragma("unroll") for (int i_ = 0; i_ < 6; ++i_) \
;         __builtin_amdgcn_global_load_lds((const GAS unsigned*)(g_ + off[i_]), (LAS unsigned*)(l_ + i_ * 256), 16, 0, 0); } while (0)
; #define R4_LOAD(o, sb_) do { const LAS float* sb = (sb_); (o).r = *(const LAS f32x4*)(sb + cgp * 4); (o).w = *(const LAS f32x4*)(sb + 64 + cgp * 4); (o).k = *(const LAS f32x4*)(sb + 128 + cgp * 4); \
;         (o).a = *(const LAS f32x4*)(sb + 256 + cgp * 4); (o).b = *(const LAS f32x4*)(sb + 320 + cgp * 4); (o).vv = sb[192 + rq * 4 + rl]; asm volatile("" ::: "memory"); } while (0)
; __device__ __forceinline__ void rwkv_prompt_wave4(LAS float* ring, const GAS float* RW, int mbase, int h, int rq, GAS float* Sout, GAS float* YR, int lane) {
;     ...
;     for (int cc = 0; cc < 3; ++cc) R4_ISSUE(cc, cc);
;     float ykeep = 0.f;
;     R4Ops oA, oB, oC, oD;
;     asm volatile("s_waitcnt vmcnt(12)" ::: "memory");
;     R4_LOAD(oA, ring); R4_LOAD(oB, ring + 384);
;     for (int ci = 0; ci < NCH; ++ci) {
;         { const int cn = ci + 3; const int cl = cn < NCH ? cn : NCH - 1; R4_ISSUE(cl, cn % R4_NS); }
;         const LAS float* cb = ring + (ci % R4_NS) * 1536; const LAS float* nb = ring + ((ci + 1) % R4_NS) * 1536;
;         R4_LOAD(oC, cb + 768);  R4_STEP(oA, 0);
;         R4_LOAD(oD, cb + 1152); R4_STEP(oB, 1);
;         asm volatile("s_waitcnt vmcnt(12)" ::: "memory");
;         R4_LOAD(oA, nb);        R4_STEP(oC, 2);
;         R4_LOAD(oB, nb + 384);  R4_STEP(oD, 3);
;         if (cgp < 4) YR[(size_t)(mbase + ci * 4 + cgp) * 512 + h * 64 + rq * 4 + rl] = ykeep;
.Lrw_nobar:
	s_lshr_b32 s0, s20, 4
	s_mul_i32 s0, s0, 0x18000
	v_subrev_u32_e32 v63, s0, v70
	v_subrev_u32_e32 v109, s0, v67
	s_lshr_b32 s0, s21, 4
	s_mul_i32 s0, s0, 0x18000
	v_subrev_u32_e32 v88, s0, v70
	v_subrev_u32_e32 v74, s0, v67
	s_waitcnt lgkmcnt(6)
	v_pk_mul_f32 v[28:29], v[44:45], v[28:29]
	s_add_i32 s0, s14, s19
	v_pk_fma_f32 v[26:27], v[42:43], v[26:27], v[28:29]
	v_add_u32_e32 v104, s0, v74
	v_add_f32_e32 v26, v26, v27
	ds_read_b128 v[72:75], v104 offset:3072
	ds_read_b128 v[76:79], v104 offset:3328
	v_add_f32_dpp v26, v26, v26 quad_perm:[1,0,3,2] row_mask:0xf bank_mask:0xf bound_ctrl:1
	ds_read_b128 v[80:83], v104 offset:3584
	ds_read_b128 v[84:87], v104 offset:4096
	v_add_f32_dpp v26, v26, v26 quad_perm:[2,3,0,1] row_mask:0xf bank_mask:0xf bound_ctrl:1
	v_pk_mul_f32 v[8:9], v[64:65], v[8:9] op_sel_hi:[0,1]
	v_pk_mul_f32 v[10:11], v[64:65], v[10:11] op_sel_hi:[0,1]
	v_add_f32_dpp v26, v26, v26 row_half_mirror row_mask:0xf bank_mask:0xf bound_ctrl:1
	v_pk_fma_f32 v[4:5], v[42:43], v[4:5], v[8:9]
	v_pk_fma_f32 v[6:7], v[44:45], v[6:7], v[10:11]
	v_add_f32_dpp v26, v26, v26 row_mirror row_mask:0xf bank_mask:0xf bound_ctrl:1
	v_add_u32_e32 v110, s0, v88
	v_pk_fma_f32 v[4:5], v[22:23], v[26:27], v[4:5] op_sel_hi:[1,0,1]
	v_pk_fma_f32 v[6:7], v[24:25], v[26:27], v[6:7] op_sel_hi:[1,0,1]
	ds_read_b128 v[88:91], v104 offset:4352
	ds_read_b32 v108, v110 offset:3840
	ds_read_b128 v[92:95], v104 offset:4608
	ds_read_b128 v[42:45], v104 offset:4864
	ds_read_b128 v[96:99], v104 offset:5120
	ds_read_b128 v[100:103], v104 offset:5632
	ds_read_b128 v[104:107], v104 offset:5888
	ds_read_b32 v110, v110 offset:5376
	s_waitcnt lgkmcnt(12)
	v_pk_mul_f32 v[2:3], v[2:3], v[6:7]
	v_pk_mul_f32 v[40:41], v[40:41], v[6:7]
	v_add_u32_e32 v63, s0, v63
	v_pk_fma_f32 v[0:1], v[0:1], v[4:5], v[2:3]
	v_pk_fma_f32 v[38:39], v[38:39], v[4:5], v[40:41]
	v_add_f32_e32 v0, v0, v1
	v_pk_mul_f32 v[30:31], v[66:67], v[30:31] op_sel_hi:[0,1]
	v_add_f32_e32 v38, v38, v39
	v_pk_mul_f32 v[32:33], v[66:67], v[32:33] op_sel_hi:[0,1]
	v_add_f32_dpp v0, v0, v0 quad_perm:[1,0,3,2] row_mask:0xf bank_mask:0xf bound_ctrl:1
	v_add_f32_dpp v38, v38, v38 quad_perm:[1,0,3,2] row_mask:0xf bank_mask:0xf bound_ctrl:1
	v_pk_fma_f32 v[18:19], v[18:19], v[4:5], v[30:31]
	v_add_f32_dpp v0, v0, v0 quad_perm:[2,3,0,1] row_mask:0xf bank_mask:0xf bound_ctrl:1
	v_add_f32_dpp v38, v38, v38 quad_perm:[2,3,0,1] row_mask:0xf bank_mask:0xf bound_ctrl:1
	v_pk_fma_f32 v[20:21], v[20:21], v[6:7], v[32:33]
	v_add_f32_dpp v0, v0, v0 row_half_mirror row_mask:0xf bank_mask:0xf bound_ctrl:1
	v_add_f32_dpp v38, v38, v38 row_half_mirror row_mask:0xf bank_mask:0xf bound_ctrl:1
	s_nop 0
	v_add_f32_dpp v0, v0, v0 row_mirror row_mask:0xf bank_mask:0xf bound_ctrl:1
	v_add_f32_dpp v38, v38, v38 row_mirror row_mask:0xf bank_mask:0xf bound_ctrl:1
	v_cndmask_b32_e32 v8, v71, v0, vcc
	v_pk_fma_f32 v[20:21], v[36:37], v[38:39], v[20:21] op_sel_hi:[1,0,1]
	v_pk_fma_f32 v[18:19], v[34:35], v[38:39], v[18:19] op_sel_hi:[1,0,1]
	v_pk_mul_f32 v[0:1], v[14:15], v[20:21]
	v_add_u32_e32 v34, s0, v109
	v_pk_fma_f32 v[0:1], v[12:13], v[18:19], v[0:1]
	s_waitcnt lgkmcnt(0)
	v_pk_mul_f32 v[12:13], v[86:87], v[20:21]
	v_add_f32_e32 v0, v0, v1
	v_pk_fma_f32 v[12:13], v[84:85], v[18:19], v[12:13]
	v_pk_mul_f32 v[80:81], v[80:81], v[108:109] op_sel_hi:[1,0]
	v_add_f32_e32 v12, v12, v13
	v_add_f32_dpp v0, v0, v0 quad_perm:[1,0,3,2] row_mask:0xf bank_mask:0xf bound_ctrl:1
	v_pk_mul_f32 v[82:83], v[82:83], v[108:109] op_sel_hi:[1,0]
	v_add_f32_dpp v12, v12, v12 quad_perm:[1,0,3,2] row_mask:0xf bank_mask:0xf bound_ctrl:1
	v_add_f32_dpp v0, v0, v0 quad_perm:[2,3,0,1] row_mask:0xf bank_mask:0xf bound_ctrl:1
	v_pk_fma_f32 v[76:77], v[76:77], v[18:19], v[80:81]
	v_add_f32_dpp v12, v12, v12 quad_perm:[2,3,0,1] row_mask:0xf bank_mask:0xf bound_ctrl:1
	v_add_f32_dpp v0, v0, v0 row_half_mirror row_mask:0xf bank_mask:0xf bound_ctrl:1
	v_pk_fma_f32 v[78:79], v[78:79], v[20:21], v[82:83]
	v_add_f32_dpp v12, v12, v12 row_half_mirror row_mask:0xf bank_mask:0xf bound_ctrl:1
	v_add_f32_dpp v0, v0, v0 row_mirror row_mask:0xf bank_mask:0xf bound_ctrl:1
	v_cndmask_b32_e64 v30, v8, v0, s[4:5]
	v_add_f32_dpp v12, v12, v12 row_mirror row_mask:0xf bank_mask:0xf bound_ctrl:1
	v_pk_fma_f32 v[76:77], v[88:89], v[12:13], v[76:77] op_sel_hi:[1,0,1]
	v_pk_fma_f32 v[78:79], v[90:91], v[12:13], v[78:79] op_sel_hi:[1,0,1]
	ds_read_b128 v[0:3], v34 offset:6144
	v_pk_mul_f32 v[12:13], v[74:75], v[78:79]
	ds_read_b128 v[4:7], v34 offset:6400
	v_pk_fma_f32 v[12:13], v[72:73], v[76:77], v[12:13]
	ds_read_b128 v[8:11], v34 offset:6656
	v_pk_mul_f32 v[72:73], v[102:103], v[78:79]
	v_add_f32_e32 v12, v12, v13
	v_pk_fma_f32 v[72:73], v[100:101], v[76:77], v[72:73]
	ds_read_b128 v[26:29], v34 offset:7168
	v_add_f32_e32 v72, v72, v73
	ds_read_b128 v[22:25], v34 offset:7424
	v_add_f32_dpp v12, v12, v12 quad_perm:[1,0,3,2] row_mask:0xf bank_mask:0xf bound_ctrl:1
	ds_read_b32 v64, v63 offset:6912
	v_add_f32_dpp v72, v72, v72 quad_perm:[1,0,3,2] row_mask:0xf bank_mask:0xf bound_ctrl:1
	v_pk_mul_f32 v[96:97], v[96:97], v[110:111] op_sel_hi:[1,0]
	v_add_f32_dpp v12, v12, v12 quad_perm:[2,3,0,1] row_mask:0xf bank_mask:0xf bound_ctrl:1
	v_add_f32_dpp v72, v72, v72 quad_perm:[2,3,0,1] row_mask:0xf bank_mask:0xf bound_ctrl:1
	v_pk_mul_f32 v[98:99], v[98:99], v[110:111] op_sel_hi:[1,0]
	v_add_f32_dpp v12, v12, v12 row_half_mirror row_mask:0xf bank_mask:0xf bound_ctrl:1
	v_add_f32_dpp v72, v72, v72 row_half_mirror row_mask:0xf bank_mask:0xf bound_ctrl:1
	v_pk_fma_f32 v[42:43], v[42:43], v[76:77], v[96:97]
	v_add_f32_dpp v12, v12, v12 row_mirror row_mask:0xf bank_mask:0xf bound_ctrl:1
	v_add_f32_dpp v72, v72, v72 row_mirror row_mask:0xf bank_mask:0xf bound_ctrl:1
	v_pk_fma_f32 v[44:45], v[44:45], v[78:79], v[98:99]
	v_cndmask_b32_e64 v71, v30, v12, s[6:7]
	v_pk_fma_f32 v[42:43], v[104:105], v[72:73], v[42:43] op_sel_hi:[1,0,1]
	v_pk_fma_f32 v[44:45], v[106:107], v[72:73], v[44:45] op_sel_hi:[1,0,1]
	ds_read_b128 v[12:15], v34 offset:7680
	v_pk_mul_f32 v[72:73], v[94:95], v[44:45]
	ds_read_b128 v[18:21], v34 offset:7936
	v_pk_fma_f32 v[72:73], v[92:93], v[42:43], v[72:73]
	ds_read_b128 v[30:33], v34 offset:8192
	v_add_f32_e32 v72, v72, v73
	ds_read_b128 v[38:41], v34 offset:8704
	ds_read_b128 v[34:37], v34 offset:8960
	v_add_f32_dpp v72, v72, v72 quad_perm:[1,0,3,2] row_mask:0xf bank_mask:0xf bound_ctrl:1
	ds_read_b32 v66, v63 offset:8448
	s_nop 0
	v_add_f32_dpp v72, v72, v72 quad_perm:[2,3,0,1] row_mask:0xf bank_mask:0xf bound_ctrl:1
	s_nop 1
	v_add_f32_dpp v72, v72, v72 row_half_mirror row_mask:0xf bank_mask:0xf bound_ctrl:1
	s_nop 1
	v_add_f32_dpp v72, v72, v72 row_mirror row_mask:0xf bank_mask:0xf bound_ctrl:1
	v_cndmask_b32_e64 v71, v71, v72, s[8:9]
	s_and_saveexec_b64 s[0:1], s[40:41]
	s_cbranch_execz .LBB0_706
	v_ashrrev_i32_e32 v63, 31, v62
	v_lshlrev_b64 v[72:73], 11, v[62:63]
	v_lshl_add_u64 v[72:73], v[60:61], 0, v[72:73]
	global_store_dword v[72:73], v71, off
	s_branch .LBB0_706

; #define R4_ISSUE(cc, slot) do { const GAS float* g_ = gp + (size_t)(cc) * 2048; LAS float* l_ = ring + (slot) * 1536; _Pragma("unroll") for (int i_ = 0; i_ < 6; ++i_) \
;         __builtin_amdgcn_global_load_lds((const GAS unsigned*)(g_ + off[i_]), (LAS unsigned*)(l_ + i_ * 256), 16, 0, 0); } while (0)
; #define R4_LOAD(o, sb_) do { const LAS float* sb = (sb_); (o).r = *(const LAS f32x4*)(sb + cgp * 4); (o).w = *(const LAS f32x4*)(sb + 64 + cgp * 4); (o).k = *(const LAS f32x4*)(sb + 128 + cgp * 4); \
;         (o).a = *(const LAS f32x4*)(sb + 256 + cgp * 4); (o).b = *(const LAS f32x4*)(sb + 320 + cgp * 4); (o).vv = sb[192 + rq * 4 + rl]; asm volatile("" ::: "memory"); } while (0)
; __device__ __forceinline__ void rwkv_prompt_wave4(LAS float* ring, const GAS float* RW, int mbase, int h, int rq, GAS float* Sout, GAS float* YR, int lane) {
;     ...
;     for (int cc = 0; cc < 3; ++cc) R4_ISSUE(cc, cc);
;     float ykeep = 0.f;
;     R4Ops oA, oB, oC, oD;
;     asm volatile("s_waitcnt vmcnt(12)" ::: "memory");
;     R4_LOAD(oA, ring); R4_LOAD(oB, ring + 384);
;     for (int ci = 0; ci < NCH; ++ci) {
;         { const int cn = ci + 3; const int cl = cn < NCH ? cn : NCH - 1; R4_ISSUE(cl, cn % R4_NS); }
.Lld_loop:
	s_cmp_ge_u32 s1, 2
	s_cbranch_scc1 .Lld_w1
	s_waitcnt vmcnt(14)
	s_branch .Lld_bar

; #define R4_ISSUE(cc, slot) do { const GAS float* g_ = gp + (size_t)(cc) * 2048; LAS float* l_ = ring + (slot) * 1536; _Pragma("unroll") for (int i_ = 0; i_ < 6; ++i_) \
;         __builtin_amdgcn_global_load_lds((const GAS unsigned*)(g_ + off[i_]), (LAS unsigned*)(l_ + i_ * 256), 16, 0, 0); } while (0)
; #define R4_LOAD(o, sb_) do { const LAS float* sb = (sb_); (o).r = *(const LAS f32x4*)(sb + cgp * 4); (o).w = *(const LAS f32x4*)(sb + 64 + cgp * 4); (o).k = *(const LAS f32x4*)(sb + 128 + cgp * 4); \
;         (o).a = *(const LAS f32x4*)(sb + 256 + cgp * 4); (o).b = *(const LAS f32x4*)(sb + 320 + cgp * 4); (o).vv = sb[192 + rq * 4 + rl]; asm volatile("" ::: "memory"); } while (0)
; __device__ __forceinline__ void rwkv_prompt_wave4(LAS float* ring, const GAS float* RW, int mbase, int h, int rq, GAS float* Sout, GAS float* YR, int lane) {
;     ...
;     for (int cc = 0; cc < 3; ++cc) R4_ISSUE(cc, cc);
;     float ykeep = 0.f;
;     R4Ops oA, oB, oC, oD;
;     asm volatile("s_waitcnt vmcnt(12)" ::: "memory");
;     R4_LOAD(oA, ring); R4_LOAD(oB, ring + 384);
;     for (int ci = 0; ci < NCH; ++ci) {
;         { const int cn = ci + 3; const int cl = cn < NCH ? cn : NCH - 1; R4_ISSUE(cl, cn % R4_NS); }
.Lld_bar:
	s_barrier
	s_mov_b32 s19, 4
	s_branch .Lld_issue
.Lld_next:
	s_sub_u32 s19, s19, 1
	s_cmp_lg_u32 s19, 0
	s_cbranch_scc1 .Lld_issue
	s_add_u32 s18, s18, 1
	s_cmp_lt_u32 s18, 0x80
	s_cbranch_scc1 .Lld_loop
	s_waitcnt vmcnt(0)
